# retention: state-update MFMAs moved before step-A barrier with pipelined tr reads, operand swap, bf16 state published via 8 ds_write_b64
# speedup vs baseline: 1.0120x; 1.0003x over previous
; #define LAS __attribute__((address_space(3)))
; __device__ __forceinline__ int lane_id_asm() { int l; asm volatile("v_mbcnt_lo_u32_b32 %0, -1, 0\n\tv_mbcnt_hi_u32_b32 %0, -1, %0" : "=v"(l)); return l; }
; __device__ __forceinline__ void ret_mfma(const Params& P, LAS unsigned char* lds, int wave) {
;     ...
;     const int lane = lane_id_asm(), t = wave * 64 + lane, q32 = lane & 31, hf = lane >> 5, i16 = lane & 15, blk = (lane >> 4) & 1;
;     const int trrow = 8 * hf + (i16 >> 2), trcol = (16 * blk + 4 * (i16 & 3)) * 2;
;     for (int unit = blockIdx.x; unit < 256; unit += gridDim.x) {
;         const int xcd_ = unit & 7, idx_ = unit >> 3, bh = xcd_ * 4 + (idx_ >> 3), slice = idx_ & 7, b = bh >> 2, hh = bh & 3;
;         const float gam = 1.f - exp2f(-5.f - (float)hh), lg = log2f(gam), g64 = exp2f(lg * 64.f);
;         for (int i = t; i < 33792 / 16; i += NTHREADS) *(LAS u32x4*)(lds + ST_OFF + i * 16) = (u32x4){0u, 0u, 0u, 0u};
;         f32x16 st[2];
; #pragma unroll
;         for (int a = 0; a < 2; ++a)
; #pragma unroll
;             for (int i = 0; i < 16; ++i) st[a][i] = 0.f;
;         const size_t rb = (size_t)b * SEQ;
;         float dec[16];
;         { const int mblk = (wave & 3) >> 1, nblk = wave & 1, n = nblk * 32 + q32;
; #pragma unroll
;           for (int i = 0; i < 16; ++i) { const int mm = mblk * 32 + 8 * (i >> 2) + 4 * hf + (i & 3); const int dist = n > mm ? n - mm : mm - n;
;               dec[i] = wave < 4 ? __builtin_amdgcn_exp2f(lg * (float)(dist - (63 - mm))) : __builtin_amdgcn_exp2f(lg * (float)(n + 1)); } }
;         u32x4 pq[4], pkk[4], pvv;
;         const int vr = t >> 3, vc = t & 7;
.LBB0_246:
	s_or_b64 exec, exec, s[50:51]
	s_add_u32 s60, s54, 0x1f000000
	s_addc_u32 s61, s55, 0
	s_cmpk_gt_i32 s2, 0xff
	s_waitcnt lgkmcnt(0)
	s_barrier
	v_mbcnt_lo_u32_b32 v0, -1, 0
	v_mbcnt_hi_u32_b32 v0, -1, v0
	s_cbranch_scc1 .LBB0_270
	v_ashrrev_i32_e32 v3, 5, v0
	v_and_b32_e32 v8, 31, v0
	v_readlane_b32 s4, v254, 4
	s_cmpk_lt_u32 s3, 0x100
	v_lshlrev_b32_e32 v5, 3, v3
	v_lshrrev_b32_e32 v2, 2, v0
	v_and_or_b32 v84, s4, 32, v8
	s_cselect_b64 s[4:5], -1, 0
	s_cmpk_gt_u32 s3, 0xff
	v_add_u32_e32 v1, s64, v0
	v_and_or_b32 v6, v2, 3, v5
	v_lshlrev_b32_e32 v2, 2, v0
	v_and_b32_e32 v4, 16, v0
	s_cselect_b64 s[10:11], -1, 0
	s_lshl_b32 s6, s33, 4
	v_and_or_b32 v2, v2, 12, v4
	s_and_b32 s6, s6, 32
	v_lshlrev_b32_e32 v86, 2, v3
	v_ashrrev_i32_e32 v88, 3, v1
	s_movk_i32 s9, 0xc0
	v_lshlrev_b32_e32 v7, 1, v2
	v_add_u32_e32 v9, s6, v86
	v_mul_lo_u32 v13, v88, s9
	s_add_i32 s6, 0, 0x10800
	v_add_u32_e32 v13, s6, v13
	v_add_u32_e32 v148, s6, v7
	s_add_i32 s6, s64, 0
	s_add_i32 s16, 0, 0x16800
	s_add_i32 s7, 0, 0x1ec00
	v_add_u32_e32 v7, s6, v7
	s_add_i32 s6, s16, s64
	v_lshlrev_b32_e32 v149, 4, v3
	v_mul_u32_u24_e32 v15, 0x210, v84
	v_lshl_add_u32 v14, v8, 1, s6
	v_add3_u32 v150, 0, v15, v149
	s_movk_i32 s6, 0x90
	v_mov_b32_e32 v15, s7
	v_add_u32_e32 v2, 1, v84
	v_mad_u32_u24 v151, v84, s6, v15
	s_add_i32 s6, s33, -4
	v_cvt_f32_ubyte0_e32 v85, v2
	v_and_b32_e32 v10, 7, v0
	v_lshlrev_b32_e32 v2, 3, v0
	v_lshlrev_b32_e32 v11, 4, v0
	s_lshr_b32 s14, s6, 1
	v_cmp_lt_u32_e64 s[6:7], 31, v0
	v_sub_u32_e32 v0, v84, v9
	v_sub_u32_e32 v16, 0, v0
	v_max_i32_e32 v16, v0, v16
	s_movk_i32 s21, 0xffc1
	v_add3_u32 v16, v9, v16, s21
	v_cvt_f32_i32_e32 v152, v16
	v_xad_u32 v16, v9, -1, v84
	v_sub_u32_e32 v17, 0, v16
	v_max_i32_e32 v16, v16, v17
	s_movk_i32 s21, 0xffc2
	v_add3_u32 v16, v9, v16, s21
	v_cvt_f32_i32_e32 v153, v16
	v_add_u32_e32 v16, -2, v0
	v_sub_u32_e32 v17, 2, v0
	v_max_i32_e32 v16, v16, v17
	s_movk_i32 s21, 0xffc3
	v_add3_u32 v16, v9, v16, s21
	v_cvt_f32_i32_e32 v154, v16
	v_add_u32_e32 v16, -3, v0
	v_sub_u32_e32 v17, 3, v0
	v_max_i32_e32 v16, v16, v17
	s_movk_i32 s21, 0xffc4
	v_add3_u32 v16, v9, v16, s21
	v_cvt_f32_i32_e32 v155, v16
	v_add_u32_e32 v16, -8, v0
	v_sub_u32_e32 v17, 8, v0
	v_max_i32_e32 v16, v16, v17
	s_movk_i32 s21, 0xffc9
	v_add3_u32 v16, v9, v16, s21
	v_cvt_f32_i32_e32 v156, v16
	v_add_u32_e32 v16, -9, v0
	v_sub_u32_e32 v17, 9, v0
	v_max_i32_e32 v16, v16, v17
	s_movk_i32 s21, 0xffca
	v_add3_u32 v16, v9, v16, s21
	v_cvt_f32_i32_e32 v157, v16
	v_add_u32_e32 v16, -10, v0
	v_sub_u32_e32 v17, 10, v0
	v_max_i32_e32 v16, v16, v17
	s_movk_i32 s21, 0xffcb
	v_add3_u32 v16, v9, v16, s21
	v_cvt_f32_i32_e32 v158, v16
	v_add_u32_e32 v16, -11, v0
	v_sub_u32_e32 v17, 11, v0
	v_max_i32_e32 v16, v16, v17
	s_movk_i32 s21, 0xffcc
	v_add3_u32 v16, v9, v16, s21
	v_cvt_f32_i32_e32 v159, v16
	v_add_u32_e32 v16, -16, v0
	v_sub_u32_e32 v17, 16, v0
	v_max_i32_e32 v16, v16, v17
	s_movk_i32 s21, 0xffd1
	v_add3_u32 v16, v9, v16, s21
	v_cvt_f32_i32_e32 v160, v16
	v_subrev_u32_e32 v16, 17, v0
	v_sub_u32_e32 v17, 17, v0
	v_max_i32_e32 v16, v16, v17
	s_movk_i32 s21, 0xffd2
	v_add3_u32 v16, v9, v16, s21
	v_cvt_f32_i32_e32 v161, v16
	v_subrev_u32_e32 v16, 18, v0
	v_sub_u32_e32 v17, 18, v0
	v_max_i32_e32 v16, v16, v17
	s_movk_i32 s21, 0xffd3
	v_add3_u32 v16, v9, v16, s21
	v_cvt_f32_i32_e32 v162, v16
	v_subrev_u32_e32 v16, 19, v0
	v_sub_u32_e32 v17, 19, v0
	v_max_i32_e32 v16, v16, v17
	s_movk_i32 s21, 0xffd4
	v_add3_u32 v16, v9, v16, s21
	v_cvt_f32_i32_e32 v163, v16
	v_subrev_u32_e32 v16, 24, v0
	v_sub_u32_e32 v17, 24, v0
	v_max_i32_e32 v16, v16, v17
	s_movk_i32 s21, 0xffd9
	v_add3_u32 v16, v9, v16, s21
	v_cvt_f32_i32_e32 v164, v16
	v_subrev_u32_e32 v16, 25, v0
	v_sub_u32_e32 v17, 25, v0
	v_max_i32_e32 v16, v16, v17
	s_movk_i32 s21, 0xffda
	v_add3_u32 v16, v9, v16, s21
	v_cvt_f32_i32_e32 v165, v16
	v_subrev_u32_e32 v16, 26, v0
	v_sub_u32_e32 v17, 26, v0
	v_max_i32_e32 v16, v16, v17
	s_movk_i32 s21, 0xffdb
	v_add3_u32 v16, v9, v16, s21
	v_cvt_f32_i32_e32 v166, v16
	v_subrev_u32_e32 v16, 27, v0
	v_sub_u32_e32 v0, 27, v0
	v_max_i32_e32 v0, v16, v0
	s_movk_i32 s21, 0xffdc
	v_add3_u32 v0, v9, v0, s21
	s_movk_i32 s8, 0x840
	s_lshr_b32 s18, s3, 7
	v_cvt_f32_i32_e32 v167, v0
	v_add_u32_e32 v0, 0x200, v1
	v_cmp_gt_i32_e64 s[0:1], s8, v1
	v_ashrrev_i32_e32 v94, 5, v0
	v_add_u32_e32 v0, 0x400, v1
	v_mul_lo_u32 v3, v3, s8
	s_mul_i32 s8, s18, 0x4200
	s_movk_i32 s17, 0x210
	v_ashrrev_i32_e32 v92, 5, v1
	v_ashrrev_i32_e32 v96, 5, v0
	v_add_u32_e32 v0, 0x600, v1
	v_add_u32_e32 v169, 0xfffffe00, v1
	v_mov_b32_e32 v1, s8
	v_and_b32_e32 v2, 0xf8, v2
	v_and_b32_e32 v12, 0x1f0, v11
	v_ashrrev_i32_e32 v98, 5, v0
	v_mad_u32_u24 v1, v8, s17, v1
	s_mov_b32 s15, 0
	v_mov_b32_e32 v91, 0
	v_lshlrev_b32_e32 v4, 3, v10
	v_add_u32_e32 v12, 0, v12
	v_lshlrev_b32_e32 v10, 4, v10
	s_lshl_b32 s19, s18, 6
	v_add_u32_e32 v5, v151, v5
	v_lshl_add_u32 v15, s14, 6, v148
	s_lshl_b32 s20, s14, 5
	v_mul_lo_u32 v0, v92, s17
	v_mul_lo_u32 v9, v94, s17
	v_mul_lo_u32 v16, v96, s17
	v_mul_lo_u32 v17, v98, s17
	v_mul_lo_u32 v168, v6, s9
	v_mul_lo_u32 v6, v6, s17
	v_lshlrev_b32_e32 v90, 1, v2
	s_add_i32 s16, s16, s68
	v_add3_u32 v1, v1, v149, 0
	v_ashrrev_i32_e32 v89, 31, v88
	v_ashrrev_i32_e32 v87, 31, v86
	v_ashrrev_i32_e32 v93, 31, v92
	v_ashrrev_i32_e32 v95, 31, v94
	v_ashrrev_i32_e32 v97, 31, v96
	v_ashrrev_i32_e32 v99, 31, v98
	v_lshl_add_u64 v[100:101], s[44:45], 0, v[90:91]
	v_add_u32_e32 v170, s16, v11
	v_add_u32_e32 v171, 0xe400, v1
	v_add_u32_e32 v172, 0x8400, v1
	s_movk_i32 s24, 0x63f
	s_mov_b32 s25, 0xc2fc0000
	s_mov_b32 s26, 0x800000
	v_lshlrev_b32_e32 v90, 1, v2
	v_lshlrev_b32_e32 v102, 1, v4
	s_lshl_b64 s[16:17], s[14:15], 2
	s_lshl_b32 s27, s20, 1
	v_add_u32_e32 v173, v12, v0
	v_add_u32_e32 v174, v12, v9
	v_add_u32_e32 v175, v12, v16
	v_add_u32_e32 v176, v12, v17
	v_add_u32_e32 v177, v13, v10
	v_add_u32_e32 v178, s19, v5
	v_add_u32_e32 v179, v7, v6
	v_add_u32_e32 v180, v14, v3
	v_add_u32_e32 v181, v15, v168
	v_mov_b32_e32 v186, v91
	v_mov_b32_e32 v187, v91
	v_mov_b32_e32 v188, v91
	v_mov_b32_e32 v189, v91
	v_mov_b32_e32 v182, 0x42800000
	v_mov_b32_e32 v183, 0x42000000
	v_mbcnt_hi_u32_b32 v184, -1, v244
	v_and_b32_e32 v243, 31, v184
	v_mul_u32_u24_e32 v243, 0x210, v243
	v_lshrrev_b32_e32 v245, 5, v184
	v_lshl_add_u32 v243, v245, 3, v243
	v_add_u32_e32 v243, s64, v243
	v_add_u32_e32 v242, 0x16800, v243
	s_mov_b32 s28, s2
	s_branch .LBB0_249

; #define LAS __attribute__((address_space(3)))
; __device__ __forceinline__ void ret_mfma(const Params& P, LAS unsigned char* lds, int wave) {
;     ...
;                 const int w4 = wave - 4, dvblk = w4 >> 1, nblk = w4 & 1, n = nblk * 32 + q32;
; #pragma unroll 4
;                 for (int ks = 0; ks < 16; ++ks) {
;                     const bf16x8 a = *(const LAS bf16x8*)(lds + ST_OFF + (dvblk * 32 + q32) * QP + ks * 32 + hf * 16);
;                     const bf16x8 bq = *(const LAS bf16x8*)(lds + Q_OFF + n * QP + ks * 32 + hf * 16);
;                     acc = __builtin_amdgcn_mfma_f32_32x32x16_bf16(a, bq, acc, 0, 0, 0);
;                 }
;                 acc = acc * dec[0];
;             }
;             __syncthreads();
;             {
; #pragma unroll
;                 for (int a = 0; a < 2; ++a) st[a] = st[a] * g64;
; #pragma unroll
;                 for (int ks = 0; ks < 4; ++ks) {
;                     bf16x8 av[2], bk;
; #pragma unroll
;                     for (int vb = 0; vb < 2; ++vb) { const LAS unsigned char* p = lds + V_OFF + (16 * ks + trrow) * VP + vb * 64 + trcol; av[vb] = tr_pair(p, p + 4 * VP); }
;                     { const LAS unsigned char* p = lds + K_OFF + (16 * ks + trrow) * QP + wave * 64 + trcol; bk = tr_pair(p, p + 4 * QP); }
; #pragma unroll
;                     for (int vb = 0; vb < 2; ++vb) st[vb] = __builtin_amdgcn_mfma_f32_32x32x16_bf16(av[vb], bk, st[vb], 0, 0, 0);
;                 }
.LBB0_257:
	v_add_u32_e32 v243, v148, v168
	ds_read_b64_tr_b16 v[226:227], v243
	ds_read_b64_tr_b16 v[228:229], v243 offset:768
	ds_read_b64_tr_b16 v[234:235], v179 offset:33792
	ds_read_b64_tr_b16 v[236:237], v179 offset:35904
	ds_read_b64_tr_b16 v[230:231], v243 offset:64
	ds_read_b64_tr_b16 v[232:233], v243 offset:832
	ds_read_b64_tr_b16 v[238:239], v243 offset:3072
	ds_read_b64_tr_b16 v[240:241], v243 offset:3840
	ds_read_b64_tr_b16 v[250:251], v179 offset:42240
	ds_read_b64_tr_b16 v[252:253], v179 offset:44352
	ds_read_b64_tr_b16 v[246:247], v243 offset:3136
	ds_read_b64_tr_b16 v[248:249], v243 offset:3904
	v_pk_mul_f32 v[0:1], v[126:127], v[0:1]
	v_pk_mul_f32 v[2:3], v[126:127], v[2:3]
	v_pk_mul_f32 v[4:5], v[126:127], v[4:5]
	v_pk_mul_f32 v[6:7], v[126:127], v[6:7]
	v_pk_mul_f32 v[8:9], v[126:127], v[8:9]
	v_pk_mul_f32 v[10:11], v[126:127], v[10:11]
	v_pk_mul_f32 v[12:13], v[126:127], v[12:13]
	v_pk_mul_f32 v[14:15], v[126:127], v[14:15]
	v_pk_mul_f32 v[16:17], v[126:127], v[16:17]
	v_pk_mul_f32 v[18:19], v[126:127], v[18:19]
	v_pk_mul_f32 v[20:21], v[126:127], v[20:21]
	v_pk_mul_f32 v[22:23], v[126:127], v[22:23]
	v_pk_mul_f32 v[24:25], v[126:127], v[24:25]
	v_pk_mul_f32 v[26:27], v[126:127], v[26:27]
	v_pk_mul_f32 v[28:29], v[126:127], v[28:29]
	v_pk_mul_f32 v[30:31], v[126:127], v[30:31]
	s_waitcnt lgkmcnt(6)
	v_mfma_f32_32x32x16_bf16 v[0:15], v[234:237], v[226:229], v[0:15]
	v_mfma_f32_32x32x16_bf16 v[16:31], v[234:237], v[230:233], v[16:31]
	ds_read_b64_tr_b16 v[226:227], v243 offset:6144
	ds_read_b64_tr_b16 v[228:229], v243 offset:6912
	ds_read_b64_tr_b16 v[234:235], v179 offset:50688
	ds_read_b64_tr_b16 v[236:237], v179 offset:52800
	ds_read_b64_tr_b16 v[230:231], v243 offset:6208
	ds_read_b64_tr_b16 v[232:233], v243 offset:6976
	s_waitcnt lgkmcnt(6)
	v_mfma_f32_32x32x16_bf16 v[0:15], v[250:253], v[238:241], v[0:15]
	v_mfma_f32_32x32x16_bf16 v[16:31], v[250:253], v[246:249], v[16:31]
	ds_read_b64_tr_b16 v[238:239], v243 offset:9216
	ds_read_b64_tr_b16 v[240:241], v243 offset:9984
	ds_read_b64_tr_b16 v[250:251], v179 offset:59136
	ds_read_b64_tr_b16 v[252:253], v179 offset:61248
	ds_read_b64_tr_b16 v[246:247], v243 offset:9280
	ds_read_b64_tr_b16 v[248:249], v243 offset:10048
	s_waitcnt lgkmcnt(6)
	v_mfma_f32_32x32x16_bf16 v[0:15], v[234:237], v[226:229], v[0:15]
	v_mfma_f32_32x32x16_bf16 v[16:31], v[234:237], v[230:233], v[16:31]
	s_waitcnt lgkmcnt(0)
	v_mfma_f32_32x32x16_bf16 v[0:15], v[250:253], v[238:241], v[0:15]
	v_mfma_f32_32x32x16_bf16 v[16:31], v[250:253], v[246:249], v[16:31]
	v_cndmask_b32_e64 v32, 0, 1, s[10:11]
	v_cmp_ne_u32_e64 s[8:9], 1, v32
	s_andn2_b64 vcc, exec, s[10:11]
	s_mov_b64 s[22:23], -1
	s_cbranch_vccnz .LBB0_261
	ds_read_b128 v[190:193], v171
	ds_read_b128 v[194:197], v150
	ds_read_b128 v[198:201], v171 offset:32
	ds_read_b128 v[202:205], v150 offset:32
	ds_read_b128 v[210:213], v171 offset:64
	ds_read_b128 v[214:217], v150 offset:64
	ds_read_b128 v[218:221], v171 offset:96
	ds_read_b128 v[222:225], v150 offset:96
	s_waitcnt lgkmcnt(6)
	v_mfma_f32_32x32x16_bf16 v[32:47], v[190:193], v[194:197], 0
	ds_read_b128 v[190:193], v171 offset:128
	ds_read_b128 v[194:197], v150 offset:128
	s_waitcnt lgkmcnt(6)
	v_mfma_f32_32x32x16_bf16 v[32:47], v[198:201], v[202:205], v[32:47]
	ds_read_b128 v[198:201], v171 offset:160
	ds_read_b128 v[202:205], v150 offset:160
	s_waitcnt lgkmcnt(6)
	v_mfma_f32_32x32x16_bf16 v[32:47], v[210:213], v[214:217], v[32:47]
	ds_read_b128 v[210:213], v171 offset:192
	ds_read_b128 v[214:217], v150 offset:192
	s_waitcnt lgkmcnt(6)
	v_mfma_f32_32x32x16_bf16 v[32:47], v[218:221], v[222:225], v[32:47]
	ds_read_b128 v[218:221], v171 offset:224
	ds_read_b128 v[222:225], v150 offset:224
	s_waitcnt lgkmcnt(6)
	v_mfma_f32_32x32x16_bf16 v[32:47], v[190:193], v[194:197], v[32:47]
	ds_read_b128 v[190:193], v171 offset:256
	ds_read_b128 v[194:197], v150 offset:256
	s_waitcnt lgkmcnt(6)
	v_mfma_f32_32x32x16_bf16 v[32:47], v[198:201], v[202:205], v[32:47]
	ds_read_b128 v[198:201], v171 offset:288
	ds_read_b128 v[202:205], v150 offset:288
	s_waitcnt lgkmcnt(6)
	v_mfma_f32_32x32x16_bf16 v[32:47], v[210:213], v[214:217], v[32:47]
	ds_read_b128 v[210:213], v171 offset:320
	ds_read_b128 v[214:217], v150 offset:320
	s_waitcnt lgkmcnt(6)
	v_mfma_f32_32x32x16_bf16 v[32:47], v[218:221], v[222:225], v[32:47]
	ds_read_b128 v[218:221], v171 offset:352
	ds_read_b128 v[222:225], v150 offset:352
	s_waitcnt lgkmcnt(6)
	v_mfma_f32_32x32x16_bf16 v[32:47], v[190:193], v[194:197], v[32:47]
	ds_read_b128 v[190:193], v171 offset:384
	ds_read_b128 v[194:197], v150 offset:384
	s_waitcnt lgkmcnt(6)
	v_mfma_f32_32x32x16_bf16 v[32:47], v[198:201], v[202:205], v[32:47]
	ds_read_b128 v[198:201], v171 offset:416
	ds_read_b128 v[202:205], v150 offset:416
	s_waitcnt lgkmcnt(6)
	v_mfma_f32_32x32x16_bf16 v[32:47], v[210:213], v[214:217], v[32:47]
	ds_read_b128 v[210:213], v171 offset:448
	ds_read_b128 v[214:217], v150 offset:448
	s_waitcnt lgkmcnt(6)
	v_mfma_f32_32x32x16_bf16 v[32:47], v[218:221], v[222:225], v[32:47]
	ds_read_b128 v[218:221], v171 offset:480
	ds_read_b128 v[222:225], v150 offset:480
	s_waitcnt lgkmcnt(6)
	v_mfma_f32_32x32x16_bf16 v[32:47], v[190:193], v[194:197], v[32:47]
	s_waitcnt lgkmcnt(4)
	v_mfma_f32_32x32x16_bf16 v[32:47], v[198:201], v[202:205], v[32:47]
	s_waitcnt lgkmcnt(2)
	v_mfma_f32_32x32x16_bf16 v[32:47], v[210:213], v[214:217], v[32:47]
	s_waitcnt lgkmcnt(0)
	v_mfma_f32_32x32x16_bf16 v[32:47], v[218:221], v[222:225], v[32:47]
	s_nop 11
	v_pk_mul_f32 v[46:47], v[142:143], v[46:47]
	v_pk_mul_f32 v[44:45], v[140:141], v[44:45]
	v_pk_mul_f32 v[42:43], v[138:139], v[42:43]
	v_pk_mul_f32 v[40:41], v[136:137], v[40:41]
	v_pk_mul_f32 v[38:39], v[134:135], v[38:39]
	v_pk_mul_f32 v[36:37], v[132:133], v[36:37]
	v_pk_mul_f32 v[34:35], v[130:131], v[34:35]
	v_pk_mul_f32 v[32:33], v[108:109], v[32:33]
	s_mov_b64 s[22:23], 0

; #define LAS __attribute__((address_space(3)))
; __device__ __forceinline__ unsigned cvt_pk_bf16(float lo, float hi) { f32x2 v = {lo, hi}; bf16x2_t b = __builtin_convertvector(v, bf16x2_t); return __builtin_bit_cast(unsigned, b); }
; __device__ __forceinline__ void ret_mfma(const Params& P, LAS unsigned char* lds, int wave) {
;     ...
; #pragma unroll
;                 for (int vb = 0; vb < 2; ++vb)
; #pragma unroll
;                     for (int i = 0; i < 16; ++i) { const int dv = vb * 32 + 8 * (i >> 2) + 4 * hf + (i & 3);
;                         *(LAS bf16_t*)(lds + ST_OFF + dv * QP + (wave * 32 + q32) * 2) = (bf16_t)(cvt_pk_bf16(st[vb][i], 0.f) & 0xffffu); }
;             }
;             if (wave >= 4) {
;                 const int w4 = wave - 4, dvblk = w4 >> 1, nblk = w4 & 1, n = nblk * 32 + q32;
; #pragma unroll
;                 for (int ks = 0; ks < 4; ++ks) {
;                     const LAS unsigned char* p = lds + V_OFF + (16 * ks + trrow) * VP + dvblk * 64 + trcol;
;                     const bf16x8 a = tr_pair(p, p + 4 * VP);
;                     const bf16x8 bs = *(const LAS bf16x8*)(lds + S_OFF + n * SP + (16 * ks + 8 * hf) * 2);
;                     acc = __builtin_amdgcn_mfma_f32_32x32x16_bf16(a, bs, acc, 0, 0, 0);
;                 }
;                 float sq = 0.f;
; #pragma unroll
;                 for (int i = 0; i < 16; ++i) sq += acc[i] * acc[i];
;                 sq += __shfl_xor(sq, 32);
;                 if (hf == 0) rssq[(r0 + n) * 64 + hh * 16 + slice * 2 + dvblk] = sq;
;                 bf16_t* op = V + (r0 + n) * 2048 + hh * 512 + slice * 64 + dvblk * 32 + 4 * hf;
; #pragma unroll
;                 for (int j = 0; j < 4; ++j) { u32x2 w; w.x = cvt_pk_bf16(acc[4 * j], acc[4 * j + 1]); w.y = cvt_pk_bf16(acc[4 * j + 2], acc[4 * j + 3]); *(u32x2*)(op + 8 * j) = w; }
.LBB0_265:
	s_waitcnt lgkmcnt(0)
	s_barrier
	s_and_b64 vcc, exec, s[8:9]
	v_cvt_pk_bf16_f32 v226, v0, v1
	v_cvt_pk_bf16_f32 v227, v2, v3
	ds_write_b64 v242, v[226:227]
	v_cvt_pk_bf16_f32 v228, v4, v5
	v_cvt_pk_bf16_f32 v229, v6, v7
	ds_write_b64 v242, v[228:229] offset:16
	v_cvt_pk_bf16_f32 v230, v8, v9
	v_cvt_pk_bf16_f32 v231, v10, v11
	ds_write_b64 v242, v[230:231] offset:32
	v_cvt_pk_bf16_f32 v232, v12, v13
	v_cvt_pk_bf16_f32 v233, v14, v15
	ds_write_b64 v242, v[232:233] offset:48
	v_cvt_pk_bf16_f32 v226, v16, v17
	v_cvt_pk_bf16_f32 v227, v18, v19
	ds_write_b64 v242, v[226:227] offset:16896
	v_cvt_pk_bf16_f32 v228, v20, v21
	v_cvt_pk_bf16_f32 v229, v22, v23
	ds_write_b64 v242, v[228:229] offset:16912
	v_cvt_pk_bf16_f32 v230, v24, v25
	v_cvt_pk_bf16_f32 v231, v26, v27
	ds_write_b64 v242, v[230:231] offset:16928
	v_cvt_pk_bf16_f32 v232, v28, v29
	v_cvt_pk_bf16_f32 v233, v30, v31
	ds_write_b64 v242, v[232:233] offset:16944
	s_waitcnt vmcnt(0)
	s_cbranch_vccnz .LBB0_254
	ds_read_b64_tr_b16 v[190:191], v181
	ds_read_b64_tr_b16 v[192:193], v181 offset:768
	v_add_u32_e32 v103, v151, v149
	ds_read_b128 v[194:197], v103
	ds_read_b64_tr_b16 v[198:199], v181 offset:3072
	ds_read_b64_tr_b16 v[200:201], v181 offset:3840
	ds_read_b128 v[202:205], v103 offset:32
	v_and_b32_e32 v107, 64, v184
	v_add_u32_e32 v107, 64, v107
	s_waitcnt lgkmcnt(0)
	v_mfma_f32_32x32x16_bf16 v[32:47], v[190:193], v[194:197], v[32:47]
	s_lshl_b32 s8, s29, 6
	s_or_b32 s8, s18, s8
	v_or_b32_e32 v146, s8, v84
	v_mfma_f32_32x32x16_bf16 v[32:47], v[198:201], v[202:205], v[32:47]
	ds_read_b64_tr_b16 v[190:191], v181 offset:6144
	ds_read_b64_tr_b16 v[192:193], v181 offset:6912
	ds_read_b128 v[194:197], v103 offset:64
	ds_read_b64_tr_b16 v[198:199], v181 offset:9216
	ds_read_b64_tr_b16 v[200:201], v181 offset:9984
	ds_read_b128 v[202:205], v103 offset:96
	v_xor_b32_e32 v103, 32, v184
	v_cmp_lt_i32_e32 vcc, v103, v107
	s_nop 1
	v_cndmask_b32_e32 v107, v184, v103, vcc
	v_lshlrev_b32_e32 v107, 2, v107
	s_waitcnt lgkmcnt(0)
	v_mfma_f32_32x32x16_bf16 v[32:47], v[190:193], v[194:197], v[32:47]
	v_mfma_f32_32x32x16_bf16 v[32:47], v[198:201], v[202:205], v[32:47]
	s_nop 11
	v_mul_f32_e32 v103, v33, v33
	v_fmac_f32_e32 v103, v32, v32
	v_fmac_f32_e32 v103, v34, v34
	v_fmac_f32_e32 v103, v35, v35
	v_fmac_f32_e32 v103, v36, v36
	v_fmac_f32_e32 v103, v37, v37
	v_fmac_f32_e32 v103, v38, v38
	v_fmac_f32_e32 v103, v39, v39
	v_fmac_f32_e32 v103, v40, v40
	v_fmac_f32_e32 v103, v41, v41
	v_fmac_f32_e32 v103, v42, v42
	v_fmac_f32_e32 v103, v43, v43
	v_fmac_f32_e32 v103, v44, v44
	v_fmac_f32_e32 v103, v45, v45
	v_fmac_f32_e32 v103, v46, v46
	v_fmac_f32_e32 v103, v47, v47
	ds_bpermute_b32 v107, v107, v103
	s_and_saveexec_b64 s[8:9], s[6:7]
	s_xor_b64 s[8:9], exec, s[8:9]
	v_mov_b32_e32 v147, s19
	s_andn2_saveexec_b64 s[8:9], s[8:9]
	s_cbranch_execz .LBB0_253
	v_mov_b32_e32 v147, s19
	v_lshlrev_b64 v[190:191], 8, v[146:147]
	s_waitcnt lgkmcnt(0)
	v_add_f32_e32 v103, v103, v107
	v_lshl_add_u64 v[190:191], s[20:21], 0, v[190:191]
	flat_store_dword v[190:191], v103
	s_branch .LBB0_253
